# ffn_w_in conversion moved from phase 11 to the start of phase 9 for every other group of eight workgroups (staggers the merge GEMM's gate/store bursts); converted matrix placed at the start of the wor
# speedup vs baseline: 1.0112x; 1.0112x over previous
.LBB0_1081:
	s_cmp_lt_i32 s68, 10
	s_cselect_b64 s[6:7], -1, 0
	s_and_b64 s[8:9], s[6:7], s[4:5]
	s_andn2_b64 vcc, exec, s[8:9]
	s_cbranch_vccnz .LBB0_1170
	s_cmpk_lg_u32 s70, 0x100
	s_cbranch_scc1 .Lp9_go
	s_bitcmp1_b32 s2, 3
	s_cbranch_scc0 .Lp9_go
	s_mov_b32 s76, s6
	s_mov_b32 s77, s8
	s_mov_b32 s78, s9
	s_mov_b32 s79, s14
	s_mov_b32 s80, s15
	s_mov_b32 s81, s18
	s_load_dwordx2 s[8:9], s[0:1], 0xd0
	s_lshr_b32 s83, s2, 4
	s_lshl_b32 s83, s83, 3
	s_and_b32 s84, s2, 7
	s_or_b32 s83, s83, s84
	v_lshlrev_b32_e32 v2, 2, v1
	v_lshlrev_b32_e32 v6, 5, v1
	v_lshrrev_b32_e32 v10, 6, v1
	v_and_b32_e32 v2, 0xfc, v2
	v_lshrrev_b32_e32 v11, 1, v1
	v_and_b32_e32 v6, 32, v6
	v_lshl_add_u32 v4, v2, 2, 0
	v_mul_u32_u24_e32 v5, 0x404, v10
	v_lshl_add_u32 v7, v11, 2, 0
	v_mul_u32_u24_e32 v8, 0x404, v6
	v_mov_b32_e32 v3, 0
	v_add_u32_e32 v12, v4, v5
	v_add_u32_e32 v13, v7, v8
	v_lshlrev_b32_e32 v4, 2, v2
	v_lshlrev_b32_e32 v2, 1, v6
	s_waitcnt vmcnt(0) lgkmcnt(0)
	s_barrier
	s_mov_b32 s4, s66
	v_mov_b32_e32 v5, v3
	s_mov_b32 s5, s67
	v_lshl_add_u64 v[6:7], s[8:9], 0, v[4:5]
	s_lshl_b32 s14, s83, 8
	s_mov_b32 s15, 0x8000
	s_movk_i32 s16, 0x5800
	v_add_u32_e32 v5, 0x2020, v12
	v_add_u32_e32 v8, 0x2028, v12
	v_add_u32_e32 v9, 0x4040, v12
	v_add_u32_e32 v14, 0x4048, v12
	v_add_u32_e32 v15, 0x6060, v12
	v_add_u32_e32 v16, 0x6068, v12
	v_add_u32_e32 v17, 0x8080, v12
	v_add_u32_e32 v18, 0x8088, v12
	v_add_u32_e32 v19, 0xa0a0, v12
	v_add_u32_e32 v20, 0xa0a8, v12
	v_add_u32_e32 v21, 0xc0c0, v12
	v_add_u32_e32 v22, 0xc0c8, v12
	v_add_u32_e32 v23, 0xe0e0, v12
	v_add_u32_e32 v24, 0xe0e8, v12
	s_mov_b32 s17, s83
.Lp9_convloop:
	s_mul_hi_i32 s6, s17, 0x2e8ba2e9
	s_lshr_b32 s7, s6, 31
	s_ashr_i32 s6, s6, 2
	s_add_i32 s7, s6, s7
	s_lshl_b32 s6, s7, 6
	s_mulk_i32 s7, 0xea00
	s_add_i32 s8, s14, s7
	s_ashr_i32 s9, s8, 31
	v_or_b32_e32 v25, s6, v10
	v_lshl_add_u64 v[26:27], s[8:9], 2, v[6:7]
	v_add_u32_e32 v28, 8, v25
	v_or_b32_e32 v29, 16, v25
	v_add_u32_e32 v30, 24, v25
	v_or_b32_e32 v31, 32, v25
	v_add_u32_e32 v32, 40, v25
	v_or_b32_e32 v33, 48, v25
	v_add_u32_e32 v34, 56, v25
	v_mad_i64_i32 v[58:59], s[18:19], v25, s16, v[26:27]
	v_mad_i64_i32 v[60:61], s[18:19], v28, s16, v[26:27]
	v_mad_i64_i32 v[62:63], s[18:19], v29, s16, v[26:27]
	v_mad_i64_i32 v[64:65], s[18:19], v30, s16, v[26:27]
	v_mad_i64_i32 v[66:67], s[18:19], v31, s16, v[26:27]
	v_mad_i64_i32 v[68:69], s[18:19], v32, s16, v[26:27]
	v_mad_i64_i32 v[70:71], s[18:19], v33, s16, v[26:27]
	v_mad_i64_i32 v[72:73], s[18:19], v34, s16, v[26:27]
	global_load_dwordx4 v[26:29], v[58:59], off
	global_load_dwordx4 v[30:33], v[60:61], off
	global_load_dwordx4 v[34:37], v[62:63], off
	global_load_dwordx4 v[38:41], v[64:65], off
	global_load_dwordx4 v[42:45], v[66:67], off
	global_load_dwordx4 v[46:49], v[68:69], off
	global_load_dwordx4 v[50:53], v[70:71], off
	global_load_dwordx4 v[54:57], v[72:73], off
	v_add_u32_e32 v58, s8, v11
	v_ashrrev_i32_e32 v59, 31, v58
	v_lshlrev_b64 v[58:59], 11, v[58:59]
	s_ashr_i32 s7, s6, 31
	v_lshl_add_u64 v[58:59], s[4:5], 0, v[58:59]
	s_addk_i32 s17, 0x80
	s_add_i32 s14, s14, s15
	v_lshl_add_u64 v[58:59], s[6:7], 1, v[58:59]
	s_cmpk_gt_i32 s17, 0x15f
	v_lshl_add_u64 v[58:59], v[58:59], 0, v[2:3]
	s_waitcnt vmcnt(7)
	ds_write2_b32 v12, v26, v27 offset1:1
	ds_write2_b32 v12, v28, v29 offset0:2 offset1:3
	s_waitcnt vmcnt(6)
	ds_write2_b32 v5, v30, v31 offset1:1
	ds_write2_b32 v8, v32, v33 offset1:1
	s_waitcnt vmcnt(5)
	ds_write2_b32 v9, v34, v35 offset1:1
	ds_write2_b32 v14, v36, v37 offset1:1
	s_waitcnt vmcnt(4)
	ds_write2_b32 v15, v38, v39 offset1:1
	ds_write2_b32 v16, v40, v41 offset1:1
	s_waitcnt vmcnt(3)
	ds_write2_b32 v17, v42, v43 offset1:1
	ds_write2_b32 v18, v44, v45 offset1:1
	s_waitcnt vmcnt(2)
	ds_write2_b32 v19, v46, v47 offset1:1
	ds_write2_b32 v20, v48, v49 offset1:1
	s_waitcnt vmcnt(1)
	ds_write2_b32 v21, v50, v51 offset1:1
	ds_write2_b32 v22, v52, v53 offset1:1
	s_waitcnt vmcnt(0)
	ds_write2_b32 v23, v54, v55 offset1:1
	ds_write2_b32 v24, v56, v57 offset1:1
	s_waitcnt lgkmcnt(0)
	s_barrier
	ds_read_b32 v25, v13
	ds_read_b32 v26, v13 offset:1028
	ds_read_b32 v27, v13 offset:2056
	ds_read_b32 v28, v13 offset:3084
	ds_read_b32 v29, v13 offset:4112
	ds_read_b32 v30, v13 offset:5140
	ds_read_b32 v31, v13 offset:6168
	ds_read_b32 v32, v13 offset:7196
	ds_read_b32 v33, v13 offset:8224
	ds_read_b32 v34, v13 offset:9252
	ds_read_b32 v35, v13 offset:10280
	ds_read_b32 v36, v13 offset:11308
	ds_read_b32 v37, v13 offset:12336
	ds_read_b32 v38, v13 offset:13364
	ds_read_b32 v39, v13 offset:14392
	ds_read_b32 v40, v13 offset:15420
	ds_read_b32 v41, v13 offset:16448
	ds_read_b32 v42, v13 offset:17476
	ds_read_b32 v43, v13 offset:18504
	ds_read_b32 v44, v13 offset:19532
	ds_read_b32 v45, v13 offset:20560
	ds_read_b32 v46, v13 offset:21588
	ds_read_b32 v47, v13 offset:22616
	ds_read_b32 v48, v13 offset:23644
	ds_read_b32 v49, v13 offset:24672
	ds_read_b32 v50, v13 offset:25700
	ds_read_b32 v51, v13 offset:26728
	ds_read_b32 v52, v13 offset:27756
	ds_read_b32 v53, v13 offset:28784
	ds_read_b32 v54, v13 offset:29812
	ds_read_b32 v55, v13 offset:30840
	ds_read_b32 v56, v13 offset:31868
	s_waitcnt lgkmcnt(14)
	v_cvt_pk_bf16_f32 v26, v25, v26
	v_cvt_pk_bf16_f32 v27, v27, v28
	v_cvt_pk_bf16_f32 v28, v29, v30
	v_cvt_pk_bf16_f32 v29, v31, v32
	v_cvt_pk_bf16_f32 v30, v33, v34
	v_cvt_pk_bf16_f32 v31, v35, v36
	v_cvt_pk_bf16_f32 v32, v37, v38
	v_cvt_pk_bf16_f32 v33, v39, v40
	v_cvt_pk_bf16_f32 v34, v41, v42
	s_waitcnt lgkmcnt(12)
	v_cvt_pk_bf16_f32 v35, v43, v44
	s_waitcnt lgkmcnt(10)
	v_cvt_pk_bf16_f32 v36, v45, v46
	s_waitcnt lgkmcnt(8)
	v_cvt_pk_bf16_f32 v37, v47, v48
	s_waitcnt lgkmcnt(6)
	v_cvt_pk_bf16_f32 v38, v49, v50
	s_waitcnt lgkmcnt(4)
	v_cvt_pk_bf16_f32 v39, v51, v52
	s_waitcnt lgkmcnt(2)
	v_cvt_pk_bf16_f32 v40, v53, v54
	s_waitcnt lgkmcnt(0)
	v_cvt_pk_bf16_f32 v41, v55, v56
	global_store_dwordx4 v[58:59], v[26:29], off
	global_store_dwordx4 v[58:59], v[30:33], off offset:16
	global_store_dwordx4 v[58:59], v[34:37], off offset:32
	global_store_dwordx4 v[58:59], v[38:41], off offset:48
	s_barrier
	s_cbranch_scc0 .Lp9_convloop
	s_mov_b32 s6, s76
	s_mov_b32 s8, s77
	s_mov_b32 s9, s78
	s_mov_b32 s14, s79
	s_mov_b32 s15, s80
	s_mov_b32 s18, s81
.Lp9_go:
	s_add_u32 s33, s66, 0xbc00000
	s_addc_u32 s54, s67, 0
	s_add_u32 s55, s66, 0x1400000
	s_addc_u32 s56, s67, 0
	s_cmpk_lt_i32 s2, 0x100
	s_cselect_b64 s[4:5], -1, 0
	s_cmpk_gt_i32 s2, 0xff
	v_readfirstlane_b32 s20, v1
	s_cbranch_scc1 .LBB0_1084
	s_ashr_i32 s6, s2, 31
	s_lshr_b32 s6, s6, 29
	s_add_i32 s6, s2, s6
	s_ashr_i32 s7, s6, 3
	s_and_b32 s6, s6, -8
	s_sub_i32 s6, s2, s6
	s_lshl_b32 s11, s6, 5
	s_mul_i32 s10, s6, 33
	s_cmp_lt_i32 s6, 0
	s_cselect_b32 s6, s10, s11
	s_add_i32 s6, s6, s7
	s_ashr_i32 s7, s6, 31
	s_lshr_b32 s7, s7, 28
	s_add_i32 s7, s6, s7
	s_ashr_i32 s10, s7, 4
	s_and_b32 s7, s7, -16
	s_sub_i32 s6, s6, s7
	s_bfe_i32 s7, s6, 0x80000
	s_bfe_u32 s7, s7, 0x2000d
	s_add_i32 s7, s6, s7
	s_lshl_b32 s11, s10, 2
	s_bfe_i32 s10, s7, 0x80000
	s_and_b32 s7, s7, 0xfc
	s_sub_i32 s6, s6, s7
	s_sext_i32_i8 s6, s6
	s_add_i32 s6, s11, s6
	s_sext_i32_i16 s12, s10
	s_ashr_i32 s7, s6, 31
	s_lshr_b32 s10, s12, 2
	s_ashr_i32 s46, s12, 2
	s_lshl_b64 s[12:13], s[6:7], 19
	s_add_u32 s48, s33, s12
	s_addc_u32 s49, s54, s13
	s_bfe_i64 s[10:11], s[10:11], 0x100000
	s_lshl_b64 s[10:11], s[10:11], 19
	s_add_u32 s50, s55, s10
	s_addc_u32 s51, s56, s11
	s_andn2_b64 vcc, exec, s[4:5]
	s_cbranch_vccz .LBB0_1085
	s_branch .LBB0_1170

.LBB0_1361:
	s_cmp_lt_i32 s68, 12
	s_cselect_b64 s[6:7], -1, 0
	s_and_b64 s[12:13], s[6:7], s[4:5]
	s_andn2_b64 vcc, exec, s[12:13]
	v_lshrrev_b32_e32 v206, 4, v1
	s_cbranch_vccnz .LBB0_1371
	s_load_dwordx8 s[4:11], s[0:1], 0xc0
	s_cmpk_lg_u32 s70, 0x100
	s_cbranch_scc1 .Lp11_ln
.Lp11_ln:
	v_and_b32_e32 v2, 60, v206
	v_lshl_add_u32 v18, s2, 5, v2
	s_movk_i32 s14, 0x4000
	v_cmp_gt_i32_e32 vcc, s14, v18
	s_and_saveexec_b64 s[14:15], vcc
	s_cbranch_execz .LBB0_1365
	v_mbcnt_lo_u32_b32 v3, -1, 0
	v_mbcnt_hi_u32_b32 v3, -1, v3
	v_and_b32_e32 v7, 64, v3
	v_add_u32_e32 v7, 64, v7
	v_xor_b32_e32 v8, 32, v3
	v_cmp_lt_i32_e32 vcc, v8, v7
	v_lshlrev_b32_e32 v2, 3, v1
	v_and_b32_e32 v2, 0x1f8, v2
	v_cndmask_b32_e32 v8, v3, v8, vcc
	v_lshlrev_b32_e32 v71, 2, v8
	v_xor_b32_e32 v8, 16, v3
	v_cmp_lt_i32_e32 vcc, v8, v7
	v_mov_b32_e32 v21, 0
	v_lshlrev_b32_e32 v20, 1, v2
	v_cndmask_b32_e32 v8, v3, v8, vcc
	v_lshlrev_b32_e32 v72, 2, v8
	v_xor_b32_e32 v8, 8, v3
	v_cmp_lt_i32_e32 vcc, v8, v7
	v_lshl_add_u64 v[4:5], s[66:67], 0, v[20:21]
	s_lshl_b32 s19, s70, 5
	v_cndmask_b32_e32 v8, v3, v8, vcc
	v_lshlrev_b32_e32 v73, 2, v8
	v_xor_b32_e32 v8, 4, v3
	v_cmp_lt_i32_e32 vcc, v8, v7
	v_lshlrev_b32_e32 v20, 2, v2
	s_waitcnt lgkmcnt(0)
	v_lshl_add_u64 v[24:25], s[4:5], 0, v[20:21]
	v_cndmask_b32_e32 v8, v3, v8, vcc
	v_lshlrev_b32_e32 v74, 2, v8
	v_xor_b32_e32 v8, 2, v3
	v_cmp_lt_i32_e32 vcc, v8, v7
	v_lshl_add_u64 v[26:27], s[6:7], 0, v[20:21]
	s_add_u32 s6, s66, 0x1a00000
	v_cndmask_b32_e32 v8, v3, v8, vcc
	v_lshlrev_b32_e32 v75, 2, v8
	v_xor_b32_e32 v8, 1, v3
	v_cmp_lt_i32_e32 vcc, v8, v7
	s_mov_b64 s[4:5], 0x9c00000
	s_mov_b64 s[16:17], 0x5c00000
	v_or_b32_e32 v6, 0x200, v2
	s_addc_u32 s7, s67, 0
	v_cndmask_b32_e32 v3, v3, v8, vcc
	v_lshl_add_u64 v[28:29], v[4:5], 0, s[4:5]
	s_mov_b64 s[4:5], 0x1c00000
	s_mov_b32 s22, 0x3727c5ac
	v_lshl_add_u64 v[22:23], v[4:5], 0, s[16:17]
	v_lshlrev_b32_e32 v76, 2, v3
	v_lshl_add_u64 v[30:31], v[4:5], 0, s[4:5]
	s_mov_b64 s[4:5], 0
	s_movk_i32 s20, 0x1fff
	s_movk_i32 s21, 0x6000
	v_mov_b64_e32 v[32:33], s[6:7]
	s_mov_b64 s[6:7], 0x4000
	s_mov_b64 s[16:17], 0x3000
	v_lshlrev_b32_e32 v20, 2, v2
	s_mov_b32 s18, 0x3a800000
	v_lshlrev_b32_e32 v34, 2, v6
	v_mov_b32_e32 v35, v21
	v_mov_b64_e32 v[36:37], s[22:23]
	s_mov_b32 s22, 0x800000
	s_movk_i32 s23, 0x3fff
	global_load_dwordx4 v[130:133], v[24:25], off
	global_load_dwordx4 v[134:137], v[24:25], off offset:16
	global_load_dwordx4 v[138:141], v[24:25], off offset:2048
	global_load_dwordx4 v[142:145], v[24:25], off offset:2064
	global_load_dwordx4 v[146:149], v[26:27], off
	global_load_dwordx4 v[150:153], v[26:27], off offset:16
	global_load_dwordx4 v[154:157], v[26:27], off offset:2048
	global_load_dwordx4 v[158:161], v[26:27], off offset:2064
	s_waitcnt vmcnt(0)

.LBB0_1365:
	s_or_b64 exec, exec, s[14:15]
	s_cmpk_lg_u32 s70, 0x100
	s_cbranch_scc1 .Lp11_conv
	s_branch .LBB0_1371
.Lp11_conv:
	v_lshlrev_b32_e32 v2, 2, v1
	v_lshlrev_b32_e32 v6, 5, v1
	v_lshrrev_b32_e32 v10, 6, v1
	v_and_b32_e32 v2, 0xfc, v2
	v_lshrrev_b32_e32 v11, 1, v1
	v_and_b32_e32 v6, 32, v6
	v_lshl_add_u32 v4, v2, 2, 0
	v_mul_u32_u24_e32 v5, 0x404, v10
	v_lshl_add_u32 v7, v11, 2, 0
	v_mul_u32_u24_e32 v8, 0x404, v6
	s_cmpk_gt_i32 s2, 0x15f
	v_mov_b32_e32 v3, 0
	v_add_u32_e32 v12, v4, v5
	v_add_u32_e32 v13, v7, v8
	v_lshlrev_b32_e32 v4, 2, v2
	v_lshlrev_b32_e32 v2, 1, v6
	s_waitcnt vmcnt(0) lgkmcnt(0)
	s_barrier
	s_cbranch_scc1 .LBB0_1368
	s_mov_b32 s4, s66
	v_mov_b32_e32 v5, v3
	s_mov_b32 s5, s67
	v_lshl_add_u64 v[6:7], s[8:9], 0, v[4:5]
	s_lshl_b32 s14, s2, 8
	s_lshl_b32 s15, s70, 8
	s_movk_i32 s16, 0x5800
	v_add_u32_e32 v5, 0x2020, v12
	v_add_u32_e32 v8, 0x2028, v12
	v_add_u32_e32 v9, 0x4040, v12
	v_add_u32_e32 v14, 0x4048, v12
	v_add_u32_e32 v15, 0x6060, v12
	v_add_u32_e32 v16, 0x6068, v12
	v_add_u32_e32 v17, 0x8080, v12
	v_add_u32_e32 v18, 0x8088, v12
	v_add_u32_e32 v19, 0xa0a0, v12
	v_add_u32_e32 v20, 0xa0a8, v12
	v_add_u32_e32 v21, 0xc0c0, v12
	v_add_u32_e32 v22, 0xc0c8, v12
	v_add_u32_e32 v23, 0xe0e0, v12
	v_add_u32_e32 v24, 0xe0e8, v12
	s_mov_b32 s17, s2

.Lp12_noconv:
	s_cmpk_gt_i32 s2, 0x57f
	v_readfirstlane_b32 s5, v1
	s_cbranch_scc1 .LBB0_1456
	v_lshrrev_b32_e32 v4, 5, v1
	v_and_b32_e32 v13, 24, v146
	v_and_b32_e32 v4, 4, v4
	v_bfe_u32 v5, v1, 2, 2
	s_add_u32 s33, s66, 0x1c00000
	v_lshlrev_b32_e32 v2, 4, v1
	v_and_b32_e32 v3, 32, v1
	v_bfe_u32 v12, v1, 2, 4
	v_or3_b32 v4, v4, v5, v13
	v_lshrrev_b32_e32 v5, 3, v1
	s_movk_i32 s4, 0x70
	s_addc_u32 s38, s67, 0
	v_bitop3_b32 v10, v2, v3, 48 bitop3:0x6c
	v_and_b32_e32 v11, 64, v1
	v_and_or_b32 v6, v5, s4, v12
	s_movk_i32 s4, 0x60
	v_add_u32_e32 v14, 0x2000, v2
	s_mov_b32 s39, s66
	v_or_b32_e32 v3, v10, v11
	v_and_or_b32 v5, v5, s4, v4
	v_lshrrev_b32_e32 v2, 7, v14
	s_movk_i32 s4, 0xf0
	s_mov_b32 s40, s67
	v_lshl_or_b32 v132, v5, 11, v3
	v_and_or_b32 v5, v2, s4, v12
	s_movk_i32 s4, 0xe0
	s_ashr_i32 s42, s2, 31
	v_and_or_b32 v2, v2, s4, v4
	s_lshr_b32 s4, s42, 29
	s_add_i32 s4, s2, s4
	s_lshr_b32 s12, s5, 6
	s_ashr_i32 s8, s4, 3
	s_and_b32 s4, s4, -8
	s_lshr_b32 s14, s5, 8
	s_lshl_b32 s41, s12, 10
	s_sub_i32 s4, s2, s4
	s_cmp_lt_i32 s4, 0
	s_movk_i32 s43, 0xb1
	s_cselect_b32 s9, s43, 0xb0
	s_mul_i32 s4, s4, s9
	s_add_i32 s4, s4, s8
	s_mul_hi_i32 s8, s4, 0x2e8ba2e9
	s_lshr_b32 s9, s8, 31
	s_ashr_i32 s8, s8, 4
	s_add_i32 s8, s8, s9
	s_lshl_b32 s9, s8, 2
	s_mulk_i32 s8, 0x58
	s_sub_i32 s8, s4, s8
	s_bfe_i32 s4, s8, 0x80000
	s_bfe_u32 s4, s4, 0x2000d
	s_add_i32 s10, s8, s4
	s_bfe_i32 s4, s10, 0x80000
	s_and_b32 s10, s10, 0xfc
	s_sub_i32 s8, s8, s10
	s_sext_i32_i8 s8, s8
	s_add_i32 s24, s9, s8
	s_sext_i32_i16 s4, s4
	s_ashr_i32 s25, s24, 31
	s_lshr_b32 s4, s4, 2
	s_lshl_b64 s[8:9], s[24:25], 19
	s_add_u32 s30, s33, s8
	s_addc_u32 s31, s38, s9
	s_bfe_i64 s[8:9], s[4:5], 0x100000
	s_lshl_b64 s[8:9], s[8:9], 18
	s_add_u32 s34, s39, s8
	s_addc_u32 s35, s40, s9
	s_add_i32 s25, s41, 0
	s_add_i32 m0, s25, 0x10000
	v_lshl_or_b32 v136, v2, 11, v3
	global_load_lds_dwordx4 v132, s[34:35]
	s_add_i32 m0, s25, 0x12000
	s_add_u32 s8, s34, 0x580000
	global_load_lds_dwordx4 v136, s[34:35]
	s_addc_u32 s9, s35, 0
	s_add_i32 m0, s25, 0x14000
	s_add_i32 s46, s25, 0x2000
	global_load_lds_dwordx4 v132, s[8:9]
	s_add_i32 m0, s25, 0x16000
	v_lshl_or_b32 v130, v6, 11, v3
	global_load_lds_dwordx4 v136, s[8:9]
	s_mov_b32 m0, s25
	s_add_u32 s8, s30, 0x40000
	v_lshl_or_b32 v134, v5, 11, v3
	global_load_lds_dwordx4 v130, s[30:31]
	s_mov_b32 m0, s46
	s_addc_u32 s9, s31, 0
	s_add_i32 s47, s25, 0x4000
	global_load_lds_dwordx4 v134, s[30:31]
	s_mov_b32 m0, s47
	s_add_i32 s48, s25, 0x6000
	global_load_lds_dwordx4 v130, s[8:9]
	s_mov_b32 m0, s48
	v_mov_b32_e32 v133, 0
	global_load_lds_dwordx4 v134, s[8:9]
	v_mov_b32_e32 v137, v133
	v_mov_b32_e32 v131, v133
	v_mov_b32_e32 v135, v133
	s_cmp_eq_u32 s14, 1
	s_mov_b32 s49, 0
	v_lshl_add_u64 v[8:9], s[34:35], 0, v[132:133]
	v_lshl_add_u64 v[6:7], s[34:35], 0, v[136:137]
	v_lshl_add_u64 v[2:3], s[30:31], 0, v[130:131]
	s_cselect_b64 s[8:9], -1, 0
	s_cmp_lg_u32 s14, 1
	v_lshl_add_u64 v[4:5], s[30:31], 0, v[134:135]
	s_cbranch_scc1 .LBB0_1443
	s_barrier
